# M1 local-state stores: permlane32_swap pairing into dwordx4 (16 stores/wave instead of 32)
# speedup vs baseline: 1.0270x; 1.0076x over previous
.LBB0_377:
	s_or_b64 exec, exec, s[0:1]
	v_add3_u32 v5, v64, v112, v65
	ds_write_b128 v5, v[0:3] offset:17280
	v_lshrrev_b32_e32 v0, 2, v67
	v_and_b32_e32 v98, 8, v0
	v_lshlrev_b32_e32 v0, 5, v68
	v_and_b32_e32 v0, 32, v0
	v_add_u32_e32 v2, v105, v0
	v_lshlrev_b32_e32 v0, 3, v104
	s_waitcnt lgkmcnt(1)
	v_lshrrev_b32_e32 v4, 2, v69
	v_and_b32_e32 v3, 24, v0
	v_lshlrev_b64 v[0:1], 15, v[96:97]
	v_lshl_add_u64 v[100:101], s[2:3], 0, v[0:1]
	v_or_b32_e32 v0, v98, v4
	v_mul_u32_u24_e32 v0, 0x120, v0
	v_add3_u32 v106, v2, v3, v0
	v_lshl_add_u32 v102, v99, 7, v106
	s_waitcnt lgkmcnt(0)
	s_barrier
	ds_read_b64_tr_b16 v[0:1], v106
	ds_read_b64_tr_b16 v[2:3], v106 offset:1152
	ds_read_b64_tr_b16 v[4:5], v106 offset:64
	ds_read_b64_tr_b16 v[6:7], v106 offset:1216
	ds_read_b64_tr_b16 v[88:89], v102 offset:18432
	ds_read_b64_tr_b16 v[90:91], v102 offset:19584
	ds_read_b64_tr_b16 v[92:93], v102 offset:18496
	ds_read_b64_tr_b16 v[94:95], v102 offset:19648
	s_waitcnt lgkmcnt(2)
	v_mfma_f32_32x32x16_bf16 v[48:63], v[0:3], v[88:91], 0
	ds_read_b64_tr_b16 v[64:65], v106 offset:4608
	ds_read_b64_tr_b16 v[66:67], v106 offset:5760
	ds_read_b64_tr_b16 v[68:69], v106 offset:4672
	ds_read_b64_tr_b16 v[70:71], v106 offset:5824
	ds_read_b64_tr_b16 v[80:81], v102 offset:23040
	ds_read_b64_tr_b16 v[82:83], v102 offset:24192
	ds_read_b64_tr_b16 v[84:85], v102 offset:23104
	ds_read_b64_tr_b16 v[86:87], v102 offset:24256
	s_mov_b64 s[4:5], 0xd202000
	s_mov_b32 s0, 0
	s_waitcnt lgkmcnt(8)
	v_mfma_f32_32x32x16_bf16 v[32:47], v[0:3], v[92:95], 0
	v_mfma_f32_32x32x16_bf16 v[16:31], v[4:7], v[88:91], 0
	v_mfma_f32_32x32x16_bf16 v[0:15], v[4:7], v[92:95], 0
	s_waitcnt lgkmcnt(2)
	v_mfma_f32_32x32x16_bf16 v[48:63], v[64:67], v[80:83], v[48:63]
	s_waitcnt lgkmcnt(0)
	v_mfma_f32_32x32x16_bf16 v[32:47], v[64:67], v[84:87], v[32:47]
	v_mfma_f32_32x32x16_bf16 v[16:31], v[68:71], v[80:83], v[16:31]
	v_mfma_f32_32x32x16_bf16 v[0:15], v[68:71], v[84:87], v[0:15]
	ds_read_b64_tr_b16 v[64:65], v106 offset:9216
	ds_read_b64_tr_b16 v[66:67], v106 offset:10368
	ds_read_b64_tr_b16 v[68:69], v106 offset:9280
	ds_read_b64_tr_b16 v[70:71], v106 offset:10432
	ds_read_b64_tr_b16 v[72:73], v102 offset:27648
	ds_read_b64_tr_b16 v[74:75], v102 offset:28800
	ds_read_b64_tr_b16 v[76:77], v102 offset:27712
	ds_read_b64_tr_b16 v[78:79], v102 offset:28864
	s_waitcnt lgkmcnt(2)
	v_mfma_f32_32x32x16_bf16 v[48:63], v[64:67], v[72:75], v[48:63]
	s_waitcnt lgkmcnt(0)
	v_mfma_f32_32x32x16_bf16 v[32:47], v[64:67], v[76:79], v[32:47]
	v_mfma_f32_32x32x16_bf16 v[16:31], v[68:71], v[72:75], v[16:31]
	v_mfma_f32_32x32x16_bf16 v[0:15], v[68:71], v[76:79], v[0:15]
	ds_read_b64_tr_b16 v[108:109], v106 offset:13824
	ds_read_b64_tr_b16 v[110:111], v106 offset:14976
	ds_read_b64_tr_b16 v[114:115], v106 offset:13888
	ds_read_b64_tr_b16 v[116:117], v106 offset:15040
	ds_read_b64_tr_b16 v[64:65], v102 offset:32256
	ds_read_b64_tr_b16 v[66:67], v102 offset:33408
	ds_read_b64_tr_b16 v[68:69], v102 offset:32320
	ds_read_b64_tr_b16 v[70:71], v102 offset:33472
	v_lshlrev_b32_e32 v102, 8, v104
	v_and_b32_e32 v102, 0x1f00, v102
	v_lshl_or_b32 v112, v99, 14, v102
	v_lshl_add_u64 v[100:101], v[100:101], 0, v[112:113]
	v_mov_b32_e32 v99, v113
	v_or_b32_e32 v112, 16, v98
	s_waitcnt lgkmcnt(2)
	v_mfma_f32_32x32x16_bf16 v[48:63], v[108:111], v[64:67], v[48:63]
	s_waitcnt lgkmcnt(0)
	v_mfma_f32_32x32x16_bf16 v[32:47], v[108:111], v[68:71], v[32:47]
	v_mfma_f32_32x32x16_bf16 v[16:31], v[114:117], v[64:67], v[16:31]
	v_mfma_f32_32x32x16_bf16 v[0:15], v[114:117], v[68:71], v[0:15]
	v_lshlrev_b32_e32 v112, 1, v98
	v_lshl_add_u64 v[102:103], v[100:101], 0, v[112:113]
	v_lshl_add_u64 v[108:109], v[102:103], 0, s[4:5]
	v_lshl_add_u64 v[102:103], v[102:103], 0, s[56:57]
	s_nop 9
	v_cvt_pk_bf16_f32 v48, v48, v49
	v_cvt_pk_bf16_f32 v49, v50, v51
	v_cvt_pk_bf16_f32 v50, v52, v53
	v_cvt_pk_bf16_f32 v51, v54, v55
	v_cvt_pk_bf16_f32 v52, v56, v57
	v_cvt_pk_bf16_f32 v53, v58, v59
	v_cvt_pk_bf16_f32 v54, v60, v61
	v_cvt_pk_bf16_f32 v55, v62, v63
	v_permlane32_swap_b32_e32 v48, v50
	v_permlane32_swap_b32_e32 v49, v51
	v_permlane32_swap_b32_e32 v52, v54
	v_permlane32_swap_b32_e32 v53, v55
	global_store_dwordx4 v[102:103], v[48:51], off
	global_store_dwordx4 v[102:103], v[52:55], off offset:32
	v_cvt_pk_bf16_f32 v32, v32, v33
	v_cvt_pk_bf16_f32 v33, v34, v35
	v_cvt_pk_bf16_f32 v34, v36, v37
	v_cvt_pk_bf16_f32 v35, v38, v39
	v_cvt_pk_bf16_f32 v36, v40, v41
	v_cvt_pk_bf16_f32 v37, v42, v43
	v_cvt_pk_bf16_f32 v38, v44, v45
	v_cvt_pk_bf16_f32 v39, v46, v47
	v_permlane32_swap_b32_e32 v32, v34
	v_permlane32_swap_b32_e32 v33, v35
	v_permlane32_swap_b32_e32 v36, v38
	v_permlane32_swap_b32_e32 v37, v39
	global_store_dwordx4 v[108:109], v[32:35], off
	global_store_dwordx4 v[108:109], v[36:39], off offset:32
	v_cvt_pk_bf16_f32 v16, v16, v17
	v_cvt_pk_bf16_f32 v17, v18, v19
	v_cvt_pk_bf16_f32 v18, v20, v21
	v_cvt_pk_bf16_f32 v19, v22, v23
	v_cvt_pk_bf16_f32 v20, v24, v25
	v_cvt_pk_bf16_f32 v21, v26, v27
	v_cvt_pk_bf16_f32 v22, v28, v29
	v_cvt_pk_bf16_f32 v23, v30, v31
	v_permlane32_swap_b32_e32 v16, v18
	v_permlane32_swap_b32_e32 v17, v19
	v_permlane32_swap_b32_e32 v20, v22
	v_permlane32_swap_b32_e32 v21, v23
	global_store_dwordx4 v[102:103], v[16:19], off offset:64
	global_store_dwordx4 v[102:103], v[20:23], off offset:96
	v_cvt_pk_bf16_f32 v0, v0, v1
	v_cvt_pk_bf16_f32 v1, v2, v3
	v_cvt_pk_bf16_f32 v2, v4, v5
	v_cvt_pk_bf16_f32 v3, v6, v7
	v_cvt_pk_bf16_f32 v4, v8, v9
	v_cvt_pk_bf16_f32 v5, v10, v11
	v_cvt_pk_bf16_f32 v6, v12, v13
	v_cvt_pk_bf16_f32 v7, v14, v15
	v_permlane32_swap_b32_e32 v0, v2
	v_permlane32_swap_b32_e32 v1, v3
	v_permlane32_swap_b32_e32 v4, v6
	v_permlane32_swap_b32_e32 v5, v7
	global_store_dwordx4 v[108:109], v[0:3], off offset:64
	global_store_dwordx4 v[108:109], v[4:7], off offset:96
	ds_read_b64_tr_b16 v[0:1], v106 offset:128
	ds_read_b64_tr_b16 v[2:3], v106 offset:1280
	ds_read_b64_tr_b16 v[4:5], v106 offset:192
	ds_read_b64_tr_b16 v[6:7], v106 offset:1344
	s_waitcnt lgkmcnt(2)
	v_mfma_f32_32x32x16_bf16 v[32:47], v[0:3], v[92:95], 0
	v_mfma_f32_32x32x16_bf16 v[48:63], v[0:3], v[88:91], 0
	s_waitcnt lgkmcnt(0)
	v_mfma_f32_32x32x16_bf16 v[16:31], v[4:7], v[88:91], 0
	v_mfma_f32_32x32x16_bf16 v[0:15], v[4:7], v[92:95], 0
	ds_read_b64_tr_b16 v[88:89], v106 offset:4736
	ds_read_b64_tr_b16 v[90:91], v106 offset:5888
	ds_read_b64_tr_b16 v[92:93], v106 offset:4800
	ds_read_b64_tr_b16 v[94:95], v106 offset:5952
	s_waitcnt lgkmcnt(2)
	v_mfma_f32_32x32x16_bf16 v[32:47], v[88:91], v[84:87], v[32:47]
	s_waitcnt lgkmcnt(0)
	v_mfma_f32_32x32x16_bf16 v[0:15], v[92:95], v[84:87], v[0:15]
	v_mfma_f32_32x32x16_bf16 v[48:63], v[88:91], v[80:83], v[48:63]
	v_mfma_f32_32x32x16_bf16 v[16:31], v[92:95], v[80:83], v[16:31]
	ds_read_b64_tr_b16 v[80:81], v106 offset:9344
	ds_read_b64_tr_b16 v[82:83], v106 offset:10496
	ds_read_b64_tr_b16 v[84:85], v106 offset:9408
	ds_read_b64_tr_b16 v[86:87], v106 offset:10560
	s_waitcnt lgkmcnt(2)
	v_mfma_f32_32x32x16_bf16 v[32:47], v[80:83], v[76:79], v[32:47]
	s_waitcnt lgkmcnt(0)
	v_mfma_f32_32x32x16_bf16 v[0:15], v[84:87], v[76:79], v[0:15]
	v_mfma_f32_32x32x16_bf16 v[48:63], v[80:83], v[72:75], v[48:63]
	v_mfma_f32_32x32x16_bf16 v[16:31], v[84:87], v[72:75], v[16:31]
	ds_read_b64_tr_b16 v[72:73], v106 offset:13952
	ds_read_b64_tr_b16 v[74:75], v106 offset:15104
	ds_read_b64_tr_b16 v[76:77], v106 offset:14016
	ds_read_b64_tr_b16 v[78:79], v106 offset:15168
	s_waitcnt lgkmcnt(2)
	v_mfma_f32_32x32x16_bf16 v[32:47], v[72:75], v[68:71], v[32:47]
	s_waitcnt lgkmcnt(0)
	v_mfma_f32_32x32x16_bf16 v[0:15], v[76:79], v[68:71], v[0:15]
	v_mfma_f32_32x32x16_bf16 v[48:63], v[72:75], v[64:67], v[48:63]
	v_mfma_f32_32x32x16_bf16 v[16:31], v[76:79], v[64:67], v[16:31]
	s_nop 15
	v_cvt_pk_bf16_f32 v48, v48, v49
	v_cvt_pk_bf16_f32 v49, v50, v51
	v_cvt_pk_bf16_f32 v50, v52, v53
	v_cvt_pk_bf16_f32 v51, v54, v55
	v_cvt_pk_bf16_f32 v52, v56, v57
	v_cvt_pk_bf16_f32 v53, v58, v59
	v_cvt_pk_bf16_f32 v54, v60, v61
	v_cvt_pk_bf16_f32 v55, v62, v63
	v_permlane32_swap_b32_e32 v48, v50
	v_permlane32_swap_b32_e32 v49, v51
	v_permlane32_swap_b32_e32 v52, v54
	v_permlane32_swap_b32_e32 v53, v55
	global_store_dwordx4 v[102:103], v[48:51], off offset:128
	global_store_dwordx4 v[102:103], v[52:55], off offset:160
	v_cvt_pk_bf16_f32 v32, v32, v33
	v_cvt_pk_bf16_f32 v33, v34, v35
	v_cvt_pk_bf16_f32 v34, v36, v37
	v_cvt_pk_bf16_f32 v35, v38, v39
	v_cvt_pk_bf16_f32 v36, v40, v41
	v_cvt_pk_bf16_f32 v37, v42, v43
	v_cvt_pk_bf16_f32 v38, v44, v45
	v_cvt_pk_bf16_f32 v39, v46, v47
	v_permlane32_swap_b32_e32 v32, v34
	v_permlane32_swap_b32_e32 v33, v35
	v_permlane32_swap_b32_e32 v36, v38
	v_permlane32_swap_b32_e32 v37, v39
	global_store_dwordx4 v[108:109], v[32:35], off offset:128
	global_store_dwordx4 v[108:109], v[36:39], off offset:160
	v_cvt_pk_bf16_f32 v16, v16, v17
	v_cvt_pk_bf16_f32 v17, v18, v19
	v_cvt_pk_bf16_f32 v18, v20, v21
	v_cvt_pk_bf16_f32 v19, v22, v23
	v_cvt_pk_bf16_f32 v20, v24, v25
	v_cvt_pk_bf16_f32 v21, v26, v27
	v_cvt_pk_bf16_f32 v22, v28, v29
	v_cvt_pk_bf16_f32 v23, v30, v31
	v_permlane32_swap_b32_e32 v16, v18
	v_permlane32_swap_b32_e32 v17, v19
	v_permlane32_swap_b32_e32 v20, v22
	v_permlane32_swap_b32_e32 v21, v23
	global_store_dwordx4 v[102:103], v[16:19], off offset:192
	global_store_dwordx4 v[102:103], v[20:23], off offset:224
	v_cvt_pk_bf16_f32 v0, v0, v1
	v_cvt_pk_bf16_f32 v1, v2, v3
	v_cvt_pk_bf16_f32 v2, v4, v5
	v_cvt_pk_bf16_f32 v3, v6, v7
	v_cvt_pk_bf16_f32 v4, v8, v9
	v_cvt_pk_bf16_f32 v5, v10, v11
	v_cvt_pk_bf16_f32 v6, v12, v13
	v_cvt_pk_bf16_f32 v7, v14, v15
	v_permlane32_swap_b32_e32 v0, v2
	v_permlane32_swap_b32_e32 v1, v3
	v_permlane32_swap_b32_e32 v4, v6
	v_permlane32_swap_b32_e32 v5, v7
	global_store_dwordx4 v[108:109], v[0:3], off offset:192
	global_store_dwordx4 v[108:109], v[4:7], off offset:224
	v_and_b32_e32 v0, 0x7f, v104
	v_lshl_add_u32 v1, v0, 1, v105
	v_mov_b32_e32 v2, 0
